# P6 epilogue: nt hint on once-read residual loads and 3 of 4 f32 output stores
# speedup vs baseline: 1.0203x; 1.0006x over previous
.LBB0_1076:
	v_mov_b32_e32 v90, v192
	s_lshl_b32 s31, s10, 8
	s_or_b32 s31, s31, s57
	v_bfe_u32 v146, v90, 4, 2
	v_lshl_or_b32 v170, v146, 3, s31
	s_lshl_b32 s31, s40, 8
	s_add_i32 s31, s31, s56
	v_ashrrev_i32_e32 v171, 31, v170
	v_lshlrev_b64 v[144:145], 2, v[170:171]
	v_and_or_b32 v188, v90, 15, s31
	v_readlane_b32 s64, v254, 2
	v_lshl_add_u64 v[84:85], s[26:27], 0, v[144:145]
	v_lshl_add_u64 v[88:89], s[28:29], 0, v[144:145]
	v_ashrrev_i32_e32 v189, 31, v188
	v_readlane_b32 s65, v254, 3
	v_readlane_b32 s66, v254, 4
	v_readlane_b32 s67, v254, 5
	v_readlane_b32 s68, v254, 6
	v_readlane_b32 s69, v254, 7
	v_readlane_b32 s70, v254, 8
	v_readlane_b32 s71, v254, 9
	v_readlane_b32 s72, v254, 10
	v_readlane_b32 s73, v254, 11
	v_readlane_b32 s74, v254, 12
	v_readlane_b32 s75, v254, 13
	v_readlane_b32 s76, v254, 14
	v_readlane_b32 s77, v254, 15
	v_readlane_b32 s78, v254, 16
	v_readlane_b32 s79, v254, 17
	global_load_dwordx4 v[80:83], v[84:85], off offset:16
	s_nop 0
	global_load_dwordx4 v[84:87], v[84:85], off
	s_nop 0
	global_load_dwordx4 v[172:175], v[88:89], off offset:16
	global_load_dwordx4 v[176:179], v[88:89], off
	v_lshlrev_b64 v[88:89], 13, v[188:189]
	s_mov_b64 s[44:45], s[64:65]
	v_readlane_b32 s64, v254, 18
	v_or_b32_e32 v92, 0x80, v170
	v_lshl_add_u64 v[88:89], s[44:45], 0, v[88:89]
	v_readlane_b32 s78, v254, 32
	v_readlane_b32 s79, v254, 33
	v_ashrrev_i32_e32 v93, 31, v92
	v_lshl_add_u64 v[88:89], v[88:89], 0, v[144:145]
	v_lshl_add_u64 v[90:91], s[78:79], 0, v[144:145]
	v_lshlrev_b64 v[92:93], 2, v[92:93]
	global_load_dwordx4 v[180:183], v[88:89], off offset:16
	global_load_dwordx4 v[184:187], v[88:89], off
	global_load_dwordx4 v[204:207], v[90:91], off offset:16
	global_load_dwordx4 v[208:211], v[90:91], off
	v_lshl_add_u64 v[94:95], s[28:29], 0, v[92:93]
	global_load_dwordx4 v[212:215], v[94:95], off
	global_load_dwordx4 v[216:219], v[94:95], off offset:16
	global_load_dwordx4 v[220:223], v[90:91], off offset:512
	global_load_dwordx4 v[224:227], v[90:91], off offset:528
	v_lshl_add_u64 v[90:91], s[26:27], 0, v[92:93]
	global_load_dwordx4 v[92:95], v[90:91], off
	v_or_b32_e32 v90, 0x84, v170
	v_ashrrev_i32_e32 v91, 31, v90
	global_load_dwordx4 v[228:231], v[88:89], off offset:528
	global_load_dwordx4 v[232:235], v[88:89], off offset:512
	v_lshl_add_u64 v[88:89], v[90:91], 2, s[26:27]
	global_load_dwordx4 v[88:91], v[88:89], off
	v_and_b32_e32 v148, 64, v200
	v_xor_b32_e32 v147, 16, v200
	v_add_u32_e32 v148, 64, v148
	v_xor_b32_e32 v149, 32, v200
	v_cmp_lt_i32_e32 vcc, v147, v148
	v_or_b32_e32 v190, 16, v188
	v_ashrrev_i32_e32 v191, 31, v190
	v_cndmask_b32_e32 v147, v200, v147, vcc
	v_cmp_lt_i32_e32 vcc, v149, v148
	v_lshlrev_b32_e32 v202, 2, v147
	v_readlane_b32 s65, v254, 19
	v_cndmask_b32_e32 v148, v200, v149, vcc
	v_cmp_eq_u32_e32 vcc, 0, v146
	v_lshlrev_b64 v[146:147], 13, v[190:191]
	v_lshl_add_u64 v[146:147], s[44:45], 0, v[146:147]
	v_lshlrev_b32_e32 v201, 2, v148
	v_lshl_add_u64 v[148:149], v[146:147], 0, v[144:145]
	global_load_dwordx4 v[152:155], v[148:149], off offset:16 nt
	global_load_dwordx4 v[156:159], v[148:149], off nt
	global_load_dwordx4 v[144:147], v[148:149], off offset:528 nt
	s_nop 0
	global_load_dwordx4 v[148:151], v[148:149], off offset:512 nt
	v_readlane_b32 s66, v254, 20
	v_readlane_b32 s67, v254, 21
	v_lshlrev_b64 v[194:195], 11, v[188:189]
	v_readlane_b32 s64, v254, 56
	v_lshl_add_u64 v[194:195], v[194:195], 0, v[170:171]
	v_readlane_b32 s65, v254, 57
	s_lshl_b32 s40, s10, 2
	s_ashr_i32 s41, s40, 31
	v_lshl_add_u64 v[236:237], v[194:195], 2, s[64:65]
	v_lshlrev_b64 v[194:195], 1, v[194:195]
	v_readlane_b32 s68, v254, 22
	v_readlane_b32 s69, v254, 23
	v_readlane_b32 s70, v254, 24
	v_readlane_b32 s71, v254, 25
	v_readlane_b32 s72, v254, 26
	v_readlane_b32 s73, v254, 27
	v_readlane_b32 s74, v254, 28
	v_readlane_b32 s75, v254, 29
	v_readlane_b32 s76, v254, 30
	v_readlane_b32 s77, v254, 31
	v_readlane_b32 s66, v254, 58
	v_readlane_b32 s67, v254, 59
	s_waitcnt vmcnt(0)
	v_pk_add_f32 v[174:175], v[174:175], 1.0 op_sel_hi:[1,0]
	v_pk_add_f32 v[176:177], v[176:177], 1.0 op_sel_hi:[1,0]
	v_pk_add_f32 v[172:173], v[172:173], 1.0 op_sel_hi:[1,0]
	v_pk_add_f32 v[178:179], v[178:179], 1.0 op_sel_hi:[1,0]
	v_pk_fma_f32 v[138:139], v[138:139], v[82:83], v[182:183]
	v_pk_fma_f32 v[142:143], v[142:143], v[86:87], v[186:187]
	v_pk_fma_f32 v[140:141], v[140:141], v[84:85], v[184:185]
	v_pk_fma_f32 v[136:137], v[136:137], v[80:81], v[180:181]
	v_pk_mul_f32 v[186:187], v[208:209], v[176:177]
	v_pk_mul_f32 v[180:181], v[206:207], v[174:175]
	v_pk_mul_f32 v[182:183], v[204:205], v[172:173]
	v_pk_add_f32 v[174:175], v[212:213], 1.0 op_sel_hi:[1,0]
	v_pk_add_f32 v[204:205], v[218:219], 1.0 op_sel_hi:[1,0]
	v_pk_mul_f32 v[184:185], v[210:211], v[178:179]
	global_store_dwordx4 v[236:237], v[140:143], off
	global_store_dwordx4 v[236:237], v[136:139], off offset:16 nt
	v_pk_mul_f32 v[178:179], v[220:221], v[174:175]
	v_pk_mul_f32 v[174:175], v[226:227], v[204:205]
	v_pk_mul_f32 v[204:205], v[186:187], v[140:141]
	v_mul_f32_e32 v141, v141, v141
	v_fmac_f32_e32 v141, v140, v140
	v_mul_f32_e32 v140, v143, v143
	v_pk_add_f32 v[172:173], v[214:215], 1.0 op_sel_hi:[1,0]
	v_pk_add_f32 v[206:207], v[216:217], 1.0 op_sel_hi:[1,0]
	v_pk_mul_f32 v[210:211], v[182:183], v[136:137]
	v_fmac_f32_e32 v140, v142, v142
	v_mul_f32_e32 v137, v137, v137
	v_pk_mul_f32 v[176:177], v[222:223], v[172:173]
	v_pk_mul_f32 v[172:173], v[224:225], v[206:207]
	v_pk_mul_f32 v[206:207], v[184:185], v[142:143]
	v_pk_mul_f32 v[208:209], v[180:181], v[138:139]
	v_add_f32_e32 v140, v141, v140
	v_fmac_f32_e32 v137, v136, v136
	v_cvt_pk_bf16_f32 v204, v204, v205
	v_cvt_pk_bf16_f32 v205, v206, v207
	v_cvt_pk_bf16_f32 v206, v210, v211
	v_cvt_pk_bf16_f32 v207, v208, v209
	v_lshl_add_u64 v[208:209], s[86:87], 0, v[194:195]
	v_add_f32_e32 v136, v140, v137
	v_mul_f32_e32 v137, v139, v139
	v_pk_fma_f32 v[134:135], v[134:135], v[94:95], v[234:235]
	v_pk_fma_f32 v[132:133], v[132:133], v[92:93], v[232:233]
	global_store_dwordx4 v[208:209], v[204:207], off
	v_fmac_f32_e32 v137, v138, v138
	v_pk_fma_f32 v[130:131], v[130:131], v[90:91], v[230:231]
	v_pk_fma_f32 v[128:129], v[128:129], v[88:89], v[228:229]
	global_store_dwordx4 v[236:237], v[132:135], off offset:512 nt
	global_store_dwordx4 v[236:237], v[128:131], off offset:528 nt
	v_pk_mul_f32 v[138:139], v[178:179], v[132:133]
	v_mul_f32_e32 v133, v133, v133
	v_fmac_f32_e32 v133, v132, v132
	v_mul_f32_e32 v132, v135, v135
	v_fmac_f32_e32 v132, v134, v134
	v_add_f32_e32 v132, v133, v132
	v_mul_f32_e32 v133, v129, v129
	v_pk_mul_f32 v[140:141], v[174:175], v[130:131]
	v_fmac_f32_e32 v133, v128, v128
	v_mul_f32_e32 v131, v131, v131
	v_add_f32_e32 v132, v132, v133
	v_fmac_f32_e32 v131, v130, v130
	v_add_f32_e32 v142, v137, v136
	v_add_f32_e32 v130, v131, v132
	v_add_f32_e32 v133, v142, v130
	v_pk_mul_f32 v[136:137], v[176:177], v[134:135]
	ds_bpermute_b32 v134, v202, v133
	v_pk_mul_f32 v[128:129], v[172:173], v[128:129]
	v_or_b32_e32 v194, 0x100, v194
	v_cvt_pk_bf16_f32 v132, v128, v129
	v_cvt_pk_bf16_f32 v130, v138, v139
	s_waitcnt lgkmcnt(0)
	v_add_f32_e32 v128, v133, v134
	ds_bpermute_b32 v129, v201, v128
	v_cvt_pk_bf16_f32 v131, v136, v137
	v_cvt_pk_bf16_f32 v133, v140, v141
	v_lshl_add_u64 v[134:135], s[86:87], 0, v[194:195]
	global_store_dwordx4 v[134:135], v[130:133], off
	s_and_saveexec_b64 s[42:43], vcc
	s_cbranch_execz .LBB0_1078
	v_lshlrev_b64 v[130:131], 7, v[188:189]
	v_lshl_add_u64 v[130:131], s[14:15], 0, v[130:131]
	v_lshl_add_u64 v[130:131], s[40:41], 2, v[130:131]
	s_lshl_b32 s10, s55, 2
	v_lshl_add_u64 v[130:131], v[130:131], 0, s[10:11]
	s_waitcnt lgkmcnt(0)
	v_add_f32_e32 v128, v128, v129
	global_store_dword v[130:131], v128, off
.LBB0_1078:
	s_or_b64 exec, exec, s[42:43]
	v_or_b32_e32 v194, 32, v188
	v_ashrrev_i32_e32 v195, 31, v194
	v_readlane_b32 s64, v254, 2
	s_waitcnt lgkmcnt(0)
	v_lshlrev_b64 v[128:129], 13, v[194:195]
	v_readlane_b32 s65, v254, 3
	v_readlane_b32 s66, v254, 4
	v_readlane_b32 s67, v254, 5
	v_lshl_add_u64 v[128:129], s[64:65], 0, v[128:129]
	v_lshl_add_u64 v[132:133], v[170:171], 2, v[128:129]
	global_load_dwordx4 v[136:139], v[132:133], off offset:16 nt
	global_load_dwordx4 v[140:143], v[132:133], off nt
	global_load_dwordx4 v[128:131], v[132:133], off offset:528 nt
	s_nop 0
	global_load_dwordx4 v[132:135], v[132:133], off offset:512 nt
	v_lshlrev_b64 v[204:205], 11, v[190:191]
	v_readlane_b32 s64, v254, 56
	v_lshl_add_u64 v[204:205], v[204:205], 0, v[170:171]
	v_readlane_b32 s65, v254, 57
	v_pk_fma_f32 v[126:127], v[126:127], v[86:87], v[158:159]
	v_pk_fma_f32 v[124:125], v[124:125], v[84:85], v[156:157]
	v_lshl_add_u64 v[156:157], v[204:205], 2, s[64:65]
	v_pk_fma_f32 v[122:123], v[122:123], v[82:83], v[154:155]
	v_pk_fma_f32 v[120:121], v[120:121], v[80:81], v[152:153]
	global_store_dwordx4 v[156:157], v[124:127], off
	global_store_dwordx4 v[156:157], v[120:123], off offset:16 nt
	v_pk_mul_f32 v[152:153], v[186:187], v[124:125]
	v_mul_f32_e32 v125, v125, v125
	v_fmac_f32_e32 v125, v124, v124
	v_mul_f32_e32 v124, v127, v127
	v_pk_mul_f32 v[154:155], v[184:185], v[126:127]
	v_pk_mul_f32 v[158:159], v[180:181], v[122:123]
	v_pk_mul_f32 v[206:207], v[182:183], v[120:121]
	v_fmac_f32_e32 v124, v126, v126
	v_mul_f32_e32 v121, v121, v121
	v_cvt_pk_bf16_f32 v152, v152, v153
	v_cvt_pk_bf16_f32 v153, v154, v155
	v_cvt_pk_bf16_f32 v155, v158, v159
	v_lshlrev_b64 v[158:159], 1, v[204:205]
	v_add_f32_e32 v124, v125, v124
	v_fmac_f32_e32 v121, v120, v120
	v_cvt_pk_bf16_f32 v154, v206, v207
	v_lshl_add_u64 v[204:205], s[86:87], 0, v[158:159]
	v_add_f32_e32 v120, v124, v121
	v_mul_f32_e32 v121, v123, v123
	v_pk_fma_f32 v[118:119], v[118:119], v[94:95], v[150:151]
	v_pk_fma_f32 v[116:117], v[116:117], v[92:93], v[148:149]
	global_store_dwordx4 v[204:205], v[152:155], off
	v_fmac_f32_e32 v121, v122, v122
	v_pk_fma_f32 v[114:115], v[114:115], v[90:91], v[146:147]
	v_pk_fma_f32 v[112:113], v[112:113], v[88:89], v[144:145]
	global_store_dwordx4 v[156:157], v[116:119], off offset:512 nt
	global_store_dwordx4 v[156:157], v[112:115], off offset:528 nt
	v_pk_mul_f32 v[122:123], v[178:179], v[116:117]
	v_mul_f32_e32 v117, v117, v117
	v_fmac_f32_e32 v117, v116, v116
	v_mul_f32_e32 v116, v119, v119
	v_fmac_f32_e32 v116, v118, v118
	v_add_f32_e32 v116, v117, v116
	v_mul_f32_e32 v117, v113, v113
	v_pk_mul_f32 v[124:125], v[174:175], v[114:115]
	v_fmac_f32_e32 v117, v112, v112
	v_mul_f32_e32 v115, v115, v115
	v_add_f32_e32 v116, v116, v117
	v_fmac_f32_e32 v115, v114, v114
	v_add_f32_e32 v126, v121, v120
	v_add_f32_e32 v114, v115, v116
	v_add_f32_e32 v117, v126, v114
	v_pk_mul_f32 v[120:121], v[176:177], v[118:119]
	ds_bpermute_b32 v118, v202, v117
	v_pk_mul_f32 v[112:113], v[172:173], v[112:113]
	v_or_b32_e32 v158, 0x100, v158
	v_cvt_pk_bf16_f32 v116, v112, v113
	v_cvt_pk_bf16_f32 v114, v122, v123
	s_waitcnt lgkmcnt(0)
	v_add_f32_e32 v112, v117, v118
	ds_bpermute_b32 v113, v201, v112
	v_cvt_pk_bf16_f32 v115, v120, v121
	v_cvt_pk_bf16_f32 v117, v124, v125
	v_lshl_add_u64 v[118:119], s[86:87], 0, v[158:159]
	v_readlane_b32 s68, v254, 6
	v_readlane_b32 s69, v254, 7
	v_readlane_b32 s70, v254, 8
	v_readlane_b32 s71, v254, 9
	v_readlane_b32 s72, v254, 10
	v_readlane_b32 s73, v254, 11
	v_readlane_b32 s74, v254, 12
	v_readlane_b32 s75, v254, 13
	v_readlane_b32 s76, v254, 14
	v_readlane_b32 s77, v254, 15
	v_readlane_b32 s78, v254, 16
	v_readlane_b32 s79, v254, 17
	v_readlane_b32 s66, v254, 58
	v_readlane_b32 s67, v254, 59
	global_store_dwordx4 v[118:119], v[114:117], off
	s_and_saveexec_b64 s[42:43], vcc
	s_cbranch_execz .LBB0_1080
	v_lshlrev_b64 v[114:115], 7, v[190:191]
	v_lshl_add_u64 v[114:115], s[14:15], 0, v[114:115]
	v_lshl_add_u64 v[114:115], s[40:41], 2, v[114:115]
	s_lshl_b32 s10, s55, 2
	v_lshl_add_u64 v[114:115], v[114:115], 0, s[10:11]
	s_waitcnt lgkmcnt(0)
	v_add_f32_e32 v112, v112, v113
	global_store_dword v[114:115], v112, off
.LBB0_1080:
	s_or_b64 exec, exec, s[42:43]
	v_or_b32_e32 v144, 48, v188
	v_ashrrev_i32_e32 v145, 31, v144
	v_readlane_b32 s64, v254, 2
	s_waitcnt lgkmcnt(0)
	v_lshlrev_b64 v[112:113], 13, v[144:145]
	v_readlane_b32 s65, v254, 3
	v_readlane_b32 s66, v254, 4
	v_readlane_b32 s67, v254, 5
	v_lshl_add_u64 v[112:113], s[64:65], 0, v[112:113]
	v_lshl_add_u64 v[116:117], v[170:171], 2, v[112:113]
	global_load_dwordx4 v[120:123], v[116:117], off offset:16 nt
	global_load_dwordx4 v[124:127], v[116:117], off nt
	global_load_dwordx4 v[112:115], v[116:117], off offset:528 nt
	s_nop 0
	global_load_dwordx4 v[116:119], v[116:117], off offset:512 nt
	v_lshlrev_b64 v[146:147], 11, v[194:195]
	v_readlane_b32 s64, v254, 56
	v_lshl_add_u64 v[146:147], v[146:147], 0, v[170:171]
	v_readlane_b32 s65, v254, 57
	s_waitcnt vmcnt(12)
	v_pk_fma_f32 v[110:111], v[110:111], v[86:87], v[142:143]
	v_pk_fma_f32 v[108:109], v[108:109], v[84:85], v[140:141]
	v_lshl_add_u64 v[140:141], v[146:147], 2, s[64:65]
	v_pk_fma_f32 v[106:107], v[106:107], v[82:83], v[138:139]
	v_pk_fma_f32 v[104:105], v[104:105], v[80:81], v[136:137]
	global_store_dwordx4 v[140:141], v[108:111], off
	global_store_dwordx4 v[140:141], v[104:107], off offset:16 nt
	v_pk_mul_f32 v[136:137], v[186:187], v[108:109]
	v_mul_f32_e32 v109, v109, v109
	v_fmac_f32_e32 v109, v108, v108
	v_mul_f32_e32 v108, v111, v111
	v_pk_mul_f32 v[138:139], v[184:185], v[110:111]
	v_pk_mul_f32 v[142:143], v[180:181], v[106:107]
	v_pk_mul_f32 v[148:149], v[182:183], v[104:105]
	v_fmac_f32_e32 v108, v110, v110
	v_mul_f32_e32 v105, v105, v105
	v_cvt_pk_bf16_f32 v136, v136, v137
	v_cvt_pk_bf16_f32 v137, v138, v139
	v_cvt_pk_bf16_f32 v139, v142, v143
	v_lshlrev_b64 v[142:143], 1, v[146:147]
	v_add_f32_e32 v108, v109, v108
	v_fmac_f32_e32 v105, v104, v104
	v_cvt_pk_bf16_f32 v138, v148, v149
	v_lshl_add_u64 v[146:147], s[86:87], 0, v[142:143]
	v_add_f32_e32 v104, v108, v105
	v_mul_f32_e32 v105, v107, v107
	s_waitcnt vmcnt(12)
	v_pk_fma_f32 v[102:103], v[102:103], v[94:95], v[134:135]
	v_pk_fma_f32 v[100:101], v[100:101], v[92:93], v[132:133]
	global_store_dwordx4 v[146:147], v[136:139], off
	v_fmac_f32_e32 v105, v106, v106
	v_pk_fma_f32 v[98:99], v[98:99], v[90:91], v[130:131]
	v_pk_fma_f32 v[96:97], v[96:97], v[88:89], v[128:129]
	global_store_dwordx4 v[140:141], v[100:103], off offset:512 nt
	global_store_dwordx4 v[140:141], v[96:99], off offset:528 nt
	v_pk_mul_f32 v[106:107], v[178:179], v[100:101]
	v_mul_f32_e32 v101, v101, v101
	v_fmac_f32_e32 v101, v100, v100
	v_mul_f32_e32 v100, v103, v103
	v_fmac_f32_e32 v100, v102, v102
	v_add_f32_e32 v100, v101, v100
	v_mul_f32_e32 v101, v97, v97
	v_pk_mul_f32 v[108:109], v[174:175], v[98:99]
	v_fmac_f32_e32 v101, v96, v96
	v_mul_f32_e32 v99, v99, v99
	v_add_f32_e32 v100, v100, v101
	v_fmac_f32_e32 v99, v98, v98
	v_add_f32_e32 v110, v105, v104
	v_add_f32_e32 v98, v99, v100
	v_add_f32_e32 v101, v110, v98
	v_pk_mul_f32 v[104:105], v[176:177], v[102:103]
	ds_bpermute_b32 v102, v202, v101
	v_pk_mul_f32 v[96:97], v[172:173], v[96:97]
	v_or_b32_e32 v142, 0x100, v142
	v_cvt_pk_bf16_f32 v100, v96, v97
	v_cvt_pk_bf16_f32 v98, v106, v107
	s_waitcnt lgkmcnt(0)
	v_add_f32_e32 v96, v101, v102
	ds_bpermute_b32 v97, v201, v96
	v_cvt_pk_bf16_f32 v99, v104, v105
	v_cvt_pk_bf16_f32 v101, v108, v109
	v_lshl_add_u64 v[102:103], s[86:87], 0, v[142:143]
	v_readlane_b32 s68, v254, 6
	v_readlane_b32 s69, v254, 7
	v_readlane_b32 s70, v254, 8
	v_readlane_b32 s71, v254, 9
	v_readlane_b32 s72, v254, 10
	v_readlane_b32 s73, v254, 11
	v_readlane_b32 s74, v254, 12
	v_readlane_b32 s75, v254, 13
	v_readlane_b32 s76, v254, 14
	v_readlane_b32 s77, v254, 15
	v_readlane_b32 s78, v254, 16
	v_readlane_b32 s79, v254, 17
	v_readlane_b32 s66, v254, 58
	v_readlane_b32 s67, v254, 59
	global_store_dwordx4 v[102:103], v[98:101], off
	s_and_saveexec_b64 s[42:43], vcc
	s_cbranch_execz .LBB0_1082
	v_lshlrev_b64 v[98:99], 7, v[194:195]
	v_lshl_add_u64 v[98:99], s[14:15], 0, v[98:99]
	v_lshl_add_u64 v[98:99], s[40:41], 2, v[98:99]
	s_lshl_b32 s10, s55, 2
	v_lshl_add_u64 v[98:99], v[98:99], 0, s[10:11]
	s_waitcnt lgkmcnt(0)
	v_add_f32_e32 v96, v96, v97
	global_store_dword v[98:99], v96, off
.LBB0_1082:
	s_or_b64 exec, exec, s[42:43]
	v_add_u32_e32 v128, 0x80, v188
	v_ashrrev_i32_e32 v129, 31, v128
	v_readlane_b32 s64, v254, 2
	s_waitcnt lgkmcnt(0)
	v_lshlrev_b64 v[96:97], 13, v[128:129]
	v_readlane_b32 s65, v254, 3
	v_readlane_b32 s66, v254, 4
	v_readlane_b32 s67, v254, 5
	v_lshl_add_u64 v[96:97], s[64:65], 0, v[96:97]
	v_lshl_add_u64 v[100:101], v[170:171], 2, v[96:97]
	global_load_dwordx4 v[104:107], v[100:101], off offset:16 nt
	global_load_dwordx4 v[108:111], v[100:101], off nt
	global_load_dwordx4 v[96:99], v[100:101], off offset:528 nt
	s_nop 0
	global_load_dwordx4 v[100:103], v[100:101], off offset:512 nt
	v_lshlrev_b64 v[130:131], 11, v[144:145]
	v_readlane_b32 s64, v254, 56
	v_lshl_add_u64 v[130:131], v[130:131], 0, v[170:171]
	v_readlane_b32 s65, v254, 57
	s_waitcnt vmcnt(12)
	v_pk_fma_f32 v[78:79], v[78:79], v[86:87], v[126:127]
	v_pk_fma_f32 v[76:77], v[76:77], v[84:85], v[124:125]
	v_lshl_add_u64 v[124:125], v[130:131], 2, s[64:65]
	v_pk_fma_f32 v[74:75], v[74:75], v[82:83], v[122:123]
	v_pk_fma_f32 v[72:73], v[72:73], v[80:81], v[120:121]
	global_store_dwordx4 v[124:125], v[76:79], off
	global_store_dwordx4 v[124:125], v[72:75], off offset:16 nt
	v_pk_mul_f32 v[120:121], v[186:187], v[76:77]
	v_mul_f32_e32 v77, v77, v77
	v_fmac_f32_e32 v77, v76, v76
	v_mul_f32_e32 v76, v79, v79
	v_pk_mul_f32 v[122:123], v[184:185], v[78:79]
	v_pk_mul_f32 v[126:127], v[180:181], v[74:75]
	v_pk_mul_f32 v[132:133], v[182:183], v[72:73]
	v_fmac_f32_e32 v76, v78, v78
	v_mul_f32_e32 v73, v73, v73
	v_cvt_pk_bf16_f32 v120, v120, v121
	v_cvt_pk_bf16_f32 v121, v122, v123
	v_cvt_pk_bf16_f32 v123, v126, v127
	v_lshlrev_b64 v[126:127], 1, v[130:131]
	v_add_f32_e32 v76, v77, v76
	v_fmac_f32_e32 v73, v72, v72
	v_cvt_pk_bf16_f32 v122, v132, v133
	v_lshl_add_u64 v[130:131], s[86:87], 0, v[126:127]
	v_add_f32_e32 v72, v76, v73
	v_mul_f32_e32 v73, v75, v75
	s_waitcnt vmcnt(12)
	v_pk_fma_f32 v[70:71], v[70:71], v[94:95], v[118:119]
	v_pk_fma_f32 v[68:69], v[68:69], v[92:93], v[116:117]
	global_store_dwordx4 v[130:131], v[120:123], off
	v_fmac_f32_e32 v73, v74, v74
	v_pk_fma_f32 v[66:67], v[66:67], v[90:91], v[114:115]
	v_pk_fma_f32 v[64:65], v[64:65], v[88:89], v[112:113]
	global_store_dwordx4 v[124:125], v[68:71], off offset:512 nt
	global_store_dwordx4 v[124:125], v[64:67], off offset:528 nt
	v_pk_mul_f32 v[74:75], v[178:179], v[68:69]
	v_mul_f32_e32 v69, v69, v69
	v_fmac_f32_e32 v69, v68, v68
	v_mul_f32_e32 v68, v71, v71
	v_fmac_f32_e32 v68, v70, v70
	v_add_f32_e32 v68, v69, v68
	v_mul_f32_e32 v69, v65, v65
	v_pk_mul_f32 v[76:77], v[174:175], v[66:67]
	v_fmac_f32_e32 v69, v64, v64
	v_mul_f32_e32 v67, v67, v67
	v_add_f32_e32 v68, v68, v69
	v_fmac_f32_e32 v67, v66, v66
	v_add_f32_e32 v78, v73, v72
	v_add_f32_e32 v66, v67, v68
	v_add_f32_e32 v69, v78, v66
	v_pk_mul_f32 v[72:73], v[176:177], v[70:71]
	ds_bpermute_b32 v70, v202, v69
	v_pk_mul_f32 v[64:65], v[172:173], v[64:65]
	v_or_b32_e32 v126, 0x100, v126
	v_cvt_pk_bf16_f32 v68, v64, v65
	v_cvt_pk_bf16_f32 v66, v74, v75
	s_waitcnt lgkmcnt(0)
	v_add_f32_e32 v64, v69, v70
	ds_bpermute_b32 v65, v201, v64
	v_cvt_pk_bf16_f32 v67, v72, v73
	v_cvt_pk_bf16_f32 v69, v76, v77
	v_lshl_add_u64 v[70:71], s[86:87], 0, v[126:127]
	v_readlane_b32 s68, v254, 6
	v_readlane_b32 s69, v254, 7
	v_readlane_b32 s70, v254, 8
	v_readlane_b32 s71, v254, 9
	v_readlane_b32 s72, v254, 10
	v_readlane_b32 s73, v254, 11
	v_readlane_b32 s74, v254, 12
	v_readlane_b32 s75, v254, 13
	v_readlane_b32 s76, v254, 14
	v_readlane_b32 s77, v254, 15
	v_readlane_b32 s78, v254, 16
	v_readlane_b32 s79, v254, 17
	v_readlane_b32 s66, v254, 58
	v_readlane_b32 s67, v254, 59
	global_store_dwordx4 v[70:71], v[66:69], off
	s_and_saveexec_b64 s[42:43], vcc
	s_cbranch_execz .LBB0_1084
	v_lshlrev_b64 v[66:67], 7, v[144:145]
	v_lshl_add_u64 v[66:67], s[14:15], 0, v[66:67]
	v_lshl_add_u64 v[66:67], s[40:41], 2, v[66:67]
	s_lshl_b32 s10, s55, 2
	v_lshl_add_u64 v[66:67], v[66:67], 0, s[10:11]
	s_waitcnt lgkmcnt(0)
	v_add_f32_e32 v64, v64, v65
	global_store_dword v[66:67], v64, off
.LBB0_1084:
	s_or_b64 exec, exec, s[42:43]
	v_or_b32_e32 v112, 16, v128
	v_ashrrev_i32_e32 v113, 31, v112
	v_readlane_b32 s64, v254, 2
	s_waitcnt lgkmcnt(0)
	v_lshlrev_b64 v[64:65], 13, v[112:113]
	v_readlane_b32 s65, v254, 3
	v_readlane_b32 s66, v254, 4
	v_readlane_b32 s67, v254, 5
	v_lshl_add_u64 v[64:65], s[64:65], 0, v[64:65]
	v_lshl_add_u64 v[68:69], v[170:171], 2, v[64:65]
	global_load_dwordx4 v[72:75], v[68:69], off offset:16 nt
	global_load_dwordx4 v[76:79], v[68:69], off nt
	global_load_dwordx4 v[64:67], v[68:69], off offset:528 nt
	s_nop 0
	global_load_dwordx4 v[68:71], v[68:69], off offset:512 nt
	v_lshlrev_b64 v[114:115], 11, v[128:129]
	v_readlane_b32 s64, v254, 56
	v_lshl_add_u64 v[114:115], v[114:115], 0, v[170:171]
	v_readlane_b32 s65, v254, 57
	s_waitcnt vmcnt(12)
	v_pk_fma_f32 v[62:63], v[62:63], v[86:87], v[110:111]
	v_pk_fma_f32 v[60:61], v[60:61], v[84:85], v[108:109]
	v_lshl_add_u64 v[108:109], v[114:115], 2, s[64:65]
	v_pk_fma_f32 v[58:59], v[58:59], v[82:83], v[106:107]
	v_pk_fma_f32 v[56:57], v[56:57], v[80:81], v[104:105]
	global_store_dwordx4 v[108:109], v[60:63], off
	global_store_dwordx4 v[108:109], v[56:59], off offset:16 nt
	v_pk_mul_f32 v[104:105], v[186:187], v[60:61]
	v_mul_f32_e32 v61, v61, v61
	v_fmac_f32_e32 v61, v60, v60
	v_mul_f32_e32 v60, v63, v63
	v_pk_mul_f32 v[106:107], v[184:185], v[62:63]
	v_pk_mul_f32 v[110:111], v[180:181], v[58:59]
	v_pk_mul_f32 v[116:117], v[182:183], v[56:57]
	v_fmac_f32_e32 v60, v62, v62
	v_mul_f32_e32 v57, v57, v57
	v_cvt_pk_bf16_f32 v104, v104, v105
	v_cvt_pk_bf16_f32 v105, v106, v107
	v_cvt_pk_bf16_f32 v107, v110, v111
	v_lshlrev_b64 v[110:111], 1, v[114:115]
	v_add_f32_e32 v60, v61, v60
	v_fmac_f32_e32 v57, v56, v56
	v_cvt_pk_bf16_f32 v106, v116, v117
	v_lshl_add_u64 v[114:115], s[86:87], 0, v[110:111]
	v_add_f32_e32 v56, v60, v57
	v_mul_f32_e32 v57, v59, v59
	s_waitcnt vmcnt(12)
	v_pk_fma_f32 v[54:55], v[54:55], v[94:95], v[102:103]
	v_pk_fma_f32 v[52:53], v[52:53], v[92:93], v[100:101]
	global_store_dwordx4 v[114:115], v[104:107], off
	v_fmac_f32_e32 v57, v58, v58
	v_pk_fma_f32 v[50:51], v[50:51], v[90:91], v[98:99]
	v_pk_fma_f32 v[48:49], v[48:49], v[88:89], v[96:97]
	global_store_dwordx4 v[108:109], v[52:55], off offset:512 nt
	global_store_dwordx4 v[108:109], v[48:51], off offset:528 nt
	v_pk_mul_f32 v[58:59], v[178:179], v[52:53]
	v_mul_f32_e32 v53, v53, v53
	v_fmac_f32_e32 v53, v52, v52
	v_mul_f32_e32 v52, v55, v55
	v_fmac_f32_e32 v52, v54, v54
	v_add_f32_e32 v52, v53, v52
	v_mul_f32_e32 v53, v49, v49
	v_pk_mul_f32 v[60:61], v[174:175], v[50:51]
	v_fmac_f32_e32 v53, v48, v48
	v_mul_f32_e32 v51, v51, v51
	v_add_f32_e32 v52, v52, v53
	v_fmac_f32_e32 v51, v50, v50
	v_add_f32_e32 v62, v57, v56
	v_add_f32_e32 v50, v51, v52
	v_add_f32_e32 v53, v62, v50
	v_pk_mul_f32 v[56:57], v[176:177], v[54:55]
	ds_bpermute_b32 v54, v202, v53
	v_pk_mul_f32 v[48:49], v[172:173], v[48:49]
	v_or_b32_e32 v110, 0x100, v110
	v_cvt_pk_bf16_f32 v52, v48, v49
	v_cvt_pk_bf16_f32 v50, v58, v59
	s_waitcnt lgkmcnt(0)
	v_add_f32_e32 v48, v53, v54
	ds_bpermute_b32 v49, v201, v48
	v_cvt_pk_bf16_f32 v51, v56, v57
	v_cvt_pk_bf16_f32 v53, v60, v61
	v_lshl_add_u64 v[54:55], s[86:87], 0, v[110:111]
	v_readlane_b32 s68, v254, 6
	v_readlane_b32 s69, v254, 7
	v_readlane_b32 s70, v254, 8
	v_readlane_b32 s71, v254, 9
	v_readlane_b32 s72, v254, 10
	v_readlane_b32 s73, v254, 11
	v_readlane_b32 s74, v254, 12
	v_readlane_b32 s75, v254, 13
	v_readlane_b32 s76, v254, 14
	v_readlane_b32 s77, v254, 15
	v_readlane_b32 s78, v254, 16
	v_readlane_b32 s79, v254, 17
	v_readlane_b32 s66, v254, 58
	v_readlane_b32 s67, v254, 59
	global_store_dwordx4 v[54:55], v[50:53], off
	s_and_saveexec_b64 s[42:43], vcc
	s_cbranch_execz .LBB0_1086
	v_lshlrev_b64 v[50:51], 7, v[128:129]
	v_lshl_add_u64 v[50:51], s[14:15], 0, v[50:51]
	v_lshl_add_u64 v[50:51], s[40:41], 2, v[50:51]
	s_lshl_b32 s10, s55, 2
	v_lshl_add_u64 v[50:51], v[50:51], 0, s[10:11]
	s_waitcnt lgkmcnt(0)
	v_add_f32_e32 v48, v48, v49
	global_store_dword v[50:51], v48, off
.LBB0_1086:
	s_or_b64 exec, exec, s[42:43]
	v_or_b32_e32 v96, 32, v128
	v_ashrrev_i32_e32 v97, 31, v96
	v_readlane_b32 s64, v254, 2
	s_waitcnt lgkmcnt(0)
	v_lshlrev_b64 v[48:49], 13, v[96:97]
	v_readlane_b32 s65, v254, 3
	v_readlane_b32 s66, v254, 4
	v_readlane_b32 s67, v254, 5
	v_lshl_add_u64 v[48:49], s[64:65], 0, v[48:49]
	v_lshl_add_u64 v[52:53], v[170:171], 2, v[48:49]
	global_load_dwordx4 v[56:59], v[52:53], off offset:16 nt
	global_load_dwordx4 v[60:63], v[52:53], off nt
	global_load_dwordx4 v[48:51], v[52:53], off offset:528 nt
	s_nop 0
	global_load_dwordx4 v[52:55], v[52:53], off offset:512 nt
	v_lshlrev_b64 v[98:99], 11, v[112:113]
	v_readlane_b32 s64, v254, 56
	v_lshl_add_u64 v[98:99], v[98:99], 0, v[170:171]
	v_readlane_b32 s65, v254, 57
	s_waitcnt vmcnt(12)
	v_pk_fma_f32 v[46:47], v[46:47], v[86:87], v[78:79]
	v_pk_fma_f32 v[44:45], v[44:45], v[84:85], v[76:77]
	v_lshl_add_u64 v[76:77], v[98:99], 2, s[64:65]
	v_pk_fma_f32 v[42:43], v[42:43], v[82:83], v[74:75]
	v_pk_fma_f32 v[40:41], v[40:41], v[80:81], v[72:73]
	global_store_dwordx4 v[76:77], v[44:47], off
	global_store_dwordx4 v[76:77], v[40:43], off offset:16 nt
	v_pk_mul_f32 v[72:73], v[186:187], v[44:45]
	v_mul_f32_e32 v45, v45, v45
	v_fmac_f32_e32 v45, v44, v44
	v_mul_f32_e32 v44, v47, v47
	v_pk_mul_f32 v[74:75], v[184:185], v[46:47]
	v_pk_mul_f32 v[78:79], v[180:181], v[42:43]
	v_pk_mul_f32 v[100:101], v[182:183], v[40:41]
	v_fmac_f32_e32 v44, v46, v46
	v_mul_f32_e32 v41, v41, v41
	v_cvt_pk_bf16_f32 v72, v72, v73
	v_cvt_pk_bf16_f32 v73, v74, v75
	v_cvt_pk_bf16_f32 v75, v78, v79
	v_lshlrev_b64 v[78:79], 1, v[98:99]
	v_add_f32_e32 v44, v45, v44
	v_fmac_f32_e32 v41, v40, v40
	v_cvt_pk_bf16_f32 v74, v100, v101
	v_lshl_add_u64 v[98:99], s[86:87], 0, v[78:79]
	v_add_f32_e32 v40, v44, v41
	v_mul_f32_e32 v41, v43, v43
	s_waitcnt vmcnt(12)
	v_pk_fma_f32 v[38:39], v[38:39], v[94:95], v[70:71]
	v_pk_fma_f32 v[36:37], v[36:37], v[92:93], v[68:69]
	global_store_dwordx4 v[98:99], v[72:75], off
	v_fmac_f32_e32 v41, v42, v42
	v_pk_fma_f32 v[34:35], v[34:35], v[90:91], v[66:67]
	v_pk_fma_f32 v[32:33], v[32:33], v[88:89], v[64:65]
	global_store_dwordx4 v[76:77], v[36:39], off offset:512 nt
	global_store_dwordx4 v[76:77], v[32:35], off offset:528 nt
	v_pk_mul_f32 v[42:43], v[178:179], v[36:37]
	v_mul_f32_e32 v37, v37, v37
	v_fmac_f32_e32 v37, v36, v36
	v_mul_f32_e32 v36, v39, v39
	v_fmac_f32_e32 v36, v38, v38
	v_add_f32_e32 v36, v37, v36
	v_mul_f32_e32 v37, v33, v33
	v_pk_mul_f32 v[44:45], v[174:175], v[34:35]
	v_fmac_f32_e32 v37, v32, v32
	v_mul_f32_e32 v35, v35, v35
	v_add_f32_e32 v36, v36, v37
	v_fmac_f32_e32 v35, v34, v34
	v_add_f32_e32 v46, v41, v40
	v_add_f32_e32 v34, v35, v36
	v_add_f32_e32 v37, v46, v34
	v_pk_mul_f32 v[40:41], v[176:177], v[38:39]
	ds_bpermute_b32 v38, v202, v37
	v_pk_mul_f32 v[32:33], v[172:173], v[32:33]
	v_or_b32_e32 v78, 0x100, v78
	v_cvt_pk_bf16_f32 v36, v32, v33
	v_cvt_pk_bf16_f32 v34, v42, v43
	s_waitcnt lgkmcnt(0)
	v_add_f32_e32 v32, v37, v38
	ds_bpermute_b32 v33, v201, v32
	v_cvt_pk_bf16_f32 v35, v40, v41
	v_cvt_pk_bf16_f32 v37, v44, v45
	v_lshl_add_u64 v[38:39], s[86:87], 0, v[78:79]
	v_readlane_b32 s68, v254, 6
	v_readlane_b32 s69, v254, 7
	v_readlane_b32 s70, v254, 8
	v_readlane_b32 s71, v254, 9
	v_readlane_b32 s72, v254, 10
	v_readlane_b32 s73, v254, 11
	v_readlane_b32 s74, v254, 12
	v_readlane_b32 s75, v254, 13
	v_readlane_b32 s76, v254, 14
	v_readlane_b32 s77, v254, 15
	v_readlane_b32 s78, v254, 16
	v_readlane_b32 s79, v254, 17
	v_readlane_b32 s66, v254, 58
	v_readlane_b32 s67, v254, 59
	global_store_dwordx4 v[38:39], v[34:37], off
	s_and_saveexec_b64 s[42:43], vcc
	s_cbranch_execz .LBB0_1088
	v_lshlrev_b64 v[34:35], 7, v[112:113]
	v_lshl_add_u64 v[34:35], s[14:15], 0, v[34:35]
	v_lshl_add_u64 v[34:35], s[40:41], 2, v[34:35]
	s_lshl_b32 s10, s55, 2
	v_lshl_add_u64 v[34:35], v[34:35], 0, s[10:11]
	s_waitcnt lgkmcnt(0)
	v_add_f32_e32 v32, v32, v33
	global_store_dword v[34:35], v32, off
.LBB0_1088:
	s_or_b64 exec, exec, s[42:43]
	v_or_b32_e32 v64, 48, v128
	v_ashrrev_i32_e32 v65, 31, v64
	v_readlane_b32 s64, v254, 2
	s_waitcnt lgkmcnt(0)
	v_lshlrev_b64 v[32:33], 13, v[64:65]
	v_readlane_b32 s65, v254, 3
	v_readlane_b32 s76, v254, 14
	v_readlane_b32 s77, v254, 15
	v_lshl_add_u64 v[32:33], s[64:65], 0, v[32:33]
	v_lshl_add_u64 v[36:37], v[170:171], 2, v[32:33]
	global_load_dwordx4 v[40:43], v[36:37], off offset:16 nt
	global_load_dwordx4 v[44:47], v[36:37], off nt
	global_load_dwordx4 v[32:35], v[36:37], off offset:528 nt
	s_nop 0
	global_load_dwordx4 v[36:39], v[36:37], off offset:512 nt
	v_readlane_b32 s78, v254, 16
	v_readlane_b32 s79, v254, 17
	v_lshlrev_b64 v[66:67], 11, v[96:97]
	v_readlane_b32 s76, v254, 56
	v_lshl_add_u64 v[66:67], v[66:67], 0, v[170:171]
	v_readlane_b32 s77, v254, 57
	s_waitcnt vmcnt(12)
	v_pk_fma_f32 v[30:31], v[30:31], v[86:87], v[62:63]
	v_pk_fma_f32 v[28:29], v[28:29], v[84:85], v[60:61]
	v_lshl_add_u64 v[60:61], v[66:67], 2, s[76:77]
	v_pk_fma_f32 v[26:27], v[26:27], v[82:83], v[58:59]
	v_pk_fma_f32 v[24:25], v[24:25], v[80:81], v[56:57]
	global_store_dwordx4 v[60:61], v[28:31], off
	global_store_dwordx4 v[60:61], v[24:27], off offset:16 nt
	v_pk_mul_f32 v[56:57], v[186:187], v[28:29]
	v_mul_f32_e32 v29, v29, v29
	v_fmac_f32_e32 v29, v28, v28
	v_mul_f32_e32 v28, v31, v31
	v_pk_mul_f32 v[58:59], v[184:185], v[30:31]
	v_pk_mul_f32 v[62:63], v[180:181], v[26:27]
	v_pk_mul_f32 v[68:69], v[182:183], v[24:25]
	v_fmac_f32_e32 v28, v30, v30
	v_mul_f32_e32 v25, v25, v25
	v_cvt_pk_bf16_f32 v56, v56, v57
	v_cvt_pk_bf16_f32 v57, v58, v59
	v_cvt_pk_bf16_f32 v59, v62, v63
	v_lshlrev_b64 v[62:63], 1, v[66:67]
	v_add_f32_e32 v28, v29, v28
	v_fmac_f32_e32 v25, v24, v24
	v_cvt_pk_bf16_f32 v58, v68, v69
	v_lshl_add_u64 v[66:67], s[86:87], 0, v[62:63]
	v_add_f32_e32 v24, v28, v25
	v_mul_f32_e32 v25, v27, v27
	s_waitcnt vmcnt(12)
	v_pk_fma_f32 v[22:23], v[22:23], v[94:95], v[54:55]
	v_pk_fma_f32 v[20:21], v[20:21], v[92:93], v[52:53]
	global_store_dwordx4 v[66:67], v[56:59], off
	v_fmac_f32_e32 v25, v26, v26
	v_pk_fma_f32 v[18:19], v[18:19], v[90:91], v[50:51]
	v_pk_fma_f32 v[16:17], v[16:17], v[88:89], v[48:49]
	global_store_dwordx4 v[60:61], v[20:23], off offset:512 nt
	global_store_dwordx4 v[60:61], v[16:19], off offset:528 nt
	v_pk_mul_f32 v[26:27], v[178:179], v[20:21]
	v_mul_f32_e32 v21, v21, v21
	v_fmac_f32_e32 v21, v20, v20
	v_mul_f32_e32 v20, v23, v23
	v_fmac_f32_e32 v20, v22, v22
	v_add_f32_e32 v20, v21, v20
	v_mul_f32_e32 v21, v17, v17
	v_pk_mul_f32 v[28:29], v[174:175], v[18:19]
	v_fmac_f32_e32 v21, v16, v16
	v_mul_f32_e32 v19, v19, v19
	v_add_f32_e32 v20, v20, v21
	v_fmac_f32_e32 v19, v18, v18
	v_add_f32_e32 v30, v25, v24
	v_add_f32_e32 v18, v19, v20
	v_add_f32_e32 v21, v30, v18
	v_pk_mul_f32 v[24:25], v[176:177], v[22:23]
	ds_bpermute_b32 v22, v202, v21
	v_pk_mul_f32 v[16:17], v[172:173], v[16:17]
	v_or_b32_e32 v62, 0x100, v62
	v_cvt_pk_bf16_f32 v20, v16, v17
	v_readlane_b32 s78, v254, 58
	s_waitcnt lgkmcnt(0)
	v_add_f32_e32 v16, v21, v22
	ds_bpermute_b32 v17, v201, v16
	v_readlane_b32 s79, v254, 59
	v_cvt_pk_bf16_f32 v18, v26, v27
	v_cvt_pk_bf16_f32 v19, v24, v25
	v_cvt_pk_bf16_f32 v21, v28, v29
	v_lshl_add_u64 v[22:23], s[86:87], 0, v[62:63]
	v_readlane_b32 s66, v254, 4
	v_readlane_b32 s67, v254, 5
	v_readlane_b32 s68, v254, 6
	v_readlane_b32 s69, v254, 7
	v_readlane_b32 s70, v254, 8
	v_readlane_b32 s71, v254, 9
	v_readlane_b32 s72, v254, 10
	v_readlane_b32 s73, v254, 11
	v_readlane_b32 s74, v254, 12
	v_readlane_b32 s75, v254, 13
	global_store_dwordx4 v[22:23], v[18:21], off
	s_and_saveexec_b64 s[42:43], vcc
	s_cbranch_execz .LBB0_1090
	v_lshlrev_b64 v[18:19], 7, v[96:97]
	v_lshl_add_u64 v[18:19], s[14:15], 0, v[18:19]
	v_lshl_add_u64 v[18:19], s[40:41], 2, v[18:19]
	s_lshl_b32 s10, s55, 2
	v_lshl_add_u64 v[18:19], v[18:19], 0, s[10:11]
	s_waitcnt lgkmcnt(0)
	v_add_f32_e32 v16, v16, v17
	global_store_dword v[18:19], v16, off
.LBB0_1090:
	s_or_b64 exec, exec, s[42:43]
	s_waitcnt lgkmcnt(0)
	v_lshlrev_b64 v[16:17], 11, v[64:65]
	v_lshl_add_u64 v[20:21], v[16:17], 0, v[170:171]
	s_waitcnt vmcnt(8)
	v_pk_fma_f32 v[14:15], v[14:15], v[86:87], v[46:47]
	v_pk_fma_f32 v[12:13], v[12:13], v[84:85], v[44:45]
	v_lshl_add_u64 v[22:23], v[20:21], 2, s[76:77]
	v_pk_fma_f32 v[10:11], v[10:11], v[82:83], v[42:43]
	v_pk_fma_f32 v[8:9], v[8:9], v[80:81], v[40:41]
	global_store_dwordx4 v[22:23], v[12:15], off
	global_store_dwordx4 v[22:23], v[8:11], off offset:16 nt
	v_pk_mul_f32 v[16:17], v[186:187], v[12:13]
	v_mul_f32_e32 v13, v13, v13
	v_fmac_f32_e32 v13, v12, v12
	v_mul_f32_e32 v12, v15, v15
	v_pk_mul_f32 v[26:27], v[182:183], v[8:9]
	v_fmac_f32_e32 v12, v14, v14
	v_mul_f32_e32 v9, v9, v9
	v_pk_mul_f32 v[18:19], v[184:185], v[14:15]
	v_pk_mul_f32 v[24:25], v[180:181], v[10:11]
	v_lshlrev_b64 v[20:21], 1, v[20:21]
	v_add_f32_e32 v12, v13, v12
	v_fmac_f32_e32 v9, v8, v8
	v_cvt_pk_bf16_f32 v16, v16, v17
	v_cvt_pk_bf16_f32 v17, v18, v19
	v_cvt_pk_bf16_f32 v18, v26, v27
	v_cvt_pk_bf16_f32 v19, v24, v25
	v_lshl_add_u64 v[24:25], s[86:87], 0, v[20:21]
	v_add_f32_e32 v8, v12, v9
	v_mul_f32_e32 v9, v11, v11
	s_waitcnt vmcnt(8)
	v_pk_fma_f32 v[6:7], v[6:7], v[94:95], v[38:39]
	v_pk_fma_f32 v[4:5], v[4:5], v[92:93], v[36:37]
	global_store_dwordx4 v[24:25], v[16:19], off
	v_fmac_f32_e32 v9, v10, v10
	v_pk_fma_f32 v[2:3], v[2:3], v[90:91], v[34:35]
	v_pk_fma_f32 v[0:1], v[0:1], v[88:89], v[32:33]
	global_store_dwordx4 v[22:23], v[4:7], off offset:512 nt
	global_store_dwordx4 v[22:23], v[0:3], off offset:528 nt
	v_pk_mul_f32 v[10:11], v[178:179], v[4:5]
	v_mul_f32_e32 v5, v5, v5
	v_fmac_f32_e32 v5, v4, v4
	v_mul_f32_e32 v4, v7, v7
	v_fmac_f32_e32 v4, v6, v6
	v_add_f32_e32 v4, v5, v4
	v_mul_f32_e32 v5, v1, v1
	v_pk_mul_f32 v[12:13], v[174:175], v[2:3]
	v_fmac_f32_e32 v5, v0, v0
	v_mul_f32_e32 v3, v3, v3
	v_add_f32_e32 v4, v4, v5
	v_fmac_f32_e32 v3, v2, v2
	v_add_f32_e32 v14, v9, v8
	v_add_f32_e32 v2, v3, v4
	v_add_f32_e32 v5, v14, v2
	v_pk_mul_f32 v[8:9], v[176:177], v[6:7]
	ds_bpermute_b32 v6, v202, v5
	v_pk_mul_f32 v[0:1], v[172:173], v[0:1]
	v_or_b32_e32 v20, 0x100, v20
	v_cvt_pk_bf16_f32 v4, v0, v1
	v_cvt_pk_bf16_f32 v2, v10, v11
	s_waitcnt lgkmcnt(0)
	v_add_f32_e32 v0, v5, v6
	ds_bpermute_b32 v1, v201, v0
	v_cvt_pk_bf16_f32 v3, v8, v9
	v_cvt_pk_bf16_f32 v5, v12, v13
	v_lshl_add_u64 v[6:7], s[86:87], 0, v[20:21]
	global_store_dwordx4 v[6:7], v[2:5], off
	s_and_saveexec_b64 s[42:43], vcc
	s_cbranch_execz .LBB0_1092
	v_lshlrev_b64 v[2:3], 7, v[64:65]
	v_lshl_add_u64 v[2:3], s[14:15], 0, v[2:3]
	v_lshl_add_u64 v[2:3], s[40:41], 2, v[2:3]
	s_lshl_b32 s10, s55, 2
	v_lshl_add_u64 v[2:3], v[2:3], 0, s[10:11]
	s_waitcnt lgkmcnt(0)
	v_add_f32_e32 v0, v0, v1
	global_store_dword v[2:3], v0, off
